# grid barrier: non-leader workgroups poll the top-level generation word directly instead of the per-XCD relay word (one hop less per barrier)
# speedup vs baseline: 1.0166x; 1.0067x over previous
; DI unsigned xb_ld(unsigned* p) { return __hip_atomic_load(p, __ATOMIC_RELAXED, __HIP_MEMORY_SCOPE_AGENT); }
; DI unsigned xb_add(unsigned* p, unsigned v) { return __hip_atomic_fetch_add(p, v, __ATOMIC_RELAXED, __HIP_MEMORY_SCOPE_AGENT); }
; #define XB_SPIN(cond, bar) do { unsigned _sp = 0; while (cond) { __builtin_amdgcn_s_sleep(1); \
;     if ((++_sp & 255u) == 0u) { if (xb_ld(&(bar)[XB_TMO])) break; if (_sp > XB_SPIN_CAP) { atomicAdd(&(bar)[XB_TMO], 1u); break; } } } } while (0)
; DI void xcd_barrier(unsigned* bar, const unsigned x, volatile LAS unsigned* st, const int tid) {
;     ...
;     const unsigned old = xb_add(&bar[XB_XSUB(x)], 1u);
;     const unsigned gen = old / nloc;
;     if (old + 1u == (gen + 1u) * nloc) {
;       __builtin_amdgcn_fence(__ATOMIC_RELEASE, "agent");
;       asm volatile("s_waitcnt vmcnt(0)" ::: "memory");
;       const unsigned og = xb_add(&bar[XB_TOP], 1u);
;       const unsigned tg = og / nx;
;       if (og + 1u == (tg + 1u) * nx) xb_add(&bar[XB_TOPGEN], 1u);
;       else XB_SPIN(xb_ld(&bar[XB_TOPGEN]) == tg, bar);
;       __builtin_amdgcn_fence(__ATOMIC_ACQUIRE, "agent");
;       xb_add(&bar[XB_XGEN(x)], 1u);
;       asm volatile("s_waitcnt vmcnt(0)" ::: "memory");
;     } else {
;       XB_SPIN(xb_ld(&bar[XB_XGEN(x)]) == gen, bar);
.LBB0_1279:
	s_or_b64 exec, exec, s[2:3]
	v_cvt_f32_u32_e32 v5, v3
	s_waitcnt vmcnt(0)
	v_readfirstlane_b32 s2, v4
	v_sub_u32_e32 v4, 0, v3
	v_rcp_iflag_f32_e32 v5, v5
	v_add_u32_e32 v6, s2, v0
	v_mul_f32_e32 v5, 0x4f7ffffe, v5
	v_cvt_u32_f32_e32 v5, v5
	v_mul_lo_u32 v0, v4, v5
	v_mul_hi_u32 v0, v5, v0
	v_add_u32_e32 v0, v5, v0
	v_mul_hi_u32 v0, v6, v0
	v_mul_lo_u32 v4, v0, v3
	v_sub_u32_e32 v4, v6, v4
	v_add_u32_e32 v5, 1, v0
	v_cmp_ge_u32_e32 vcc, v4, v3
	s_nop 1
	v_cndmask_b32_e32 v0, v0, v5, vcc
	v_sub_u32_e32 v5, v4, v3
	v_cndmask_b32_e32 v4, v4, v5, vcc
	v_add_u32_e32 v5, 1, v0
	v_cmp_ge_u32_e32 vcc, v4, v3
	v_add_u32_e32 v4, 1, v6
	s_nop 0
	v_cndmask_b32_e32 v0, v0, v5, vcc
	v_mul_lo_u32 v5, v3, v0
	v_add_u32_e32 v3, v5, v3
	v_cmp_ne_u32_e32 vcc, v4, v3
	s_and_saveexec_b64 s[2:3], vcc
	s_xor_b64 s[2:3], exec, s[2:3]
	s_cbranch_execz .LBB0_1293
	v_readlane_b32 s4, v252, 58
	v_readlane_b32 s5, v252, 59
	s_waitcnt lgkmcnt(0)
	s_nop 3
	global_load_dword v2, v1, s[4:5] sc1
	s_waitcnt vmcnt(0)
	v_cmp_eq_u32_e32 vcc, v2, v0
	s_and_saveexec_b64 s[4:5], vcc
	s_cbranch_execz .LBB0_1292
	s_mov_b32 s16, 1
	s_mov_b64 s[6:7], 0
	s_branch .LBB0_1283
